# SwiGLU epilogue: cache per-lane rstd (8 values) in unused LDS tail keyed by row tile pm; later units of same CU skip rs loads + 1/sqrt chains
# speedup vs baseline: 1.0522x; 1.0109x over previous
.LBB0_857:
	s_lshl_b32 s34, s70, 17
	s_add_u32 s22, s8, 0x6b00000
	s_addc_u32 s23, s9, 0
	s_lshl_b64 s[24:25], s[34:35], 2
	s_add_u32 s24, s8, s24
	s_addc_u32 s25, s9, s25
	s_add_u32 s24, s24, 0x50000
	s_addc_u32 s25, s25, 0
	s_lshl_b32 s28, s28, 5
	s_and_b32 s31, s28, 0x60
	s_add_i32 m0, s52, 0x18000
	v_lshl_add_u64 v[10:11], v[10:11], 0, s[16:17]
	s_lshl_b32 s30, s27, 13
	s_lshl_b32 s42, s31, 7
	s_waitcnt vmcnt(2)
	s_barrier
	global_load_lds_dwordx4 v[10:11], off
	v_lshl_add_u64 v[8:9], v[8:9], 0, s[16:17]
	s_add_i32 m0, s52, 0x1a000
	s_add_i32 s34, s52, 0x8000
	s_add_i32 s56, s52, 0xa000
	global_load_lds_dwordx4 v[8:9], off
	v_lshl_add_u64 v[4:5], v[4:5], 0, s[16:17]
	s_mov_b32 m0, s34
	s_add_u32 s28, s18, 0x40080
	global_load_lds_dwordx4 v[4:5], off
	v_lshl_add_u64 v[4:5], v[6:7], 0, s[16:17]
	s_mov_b32 m0, s56
	s_addc_u32 s29, s19, 0
	global_load_lds_dwordx4 v[4:5], off
	s_add_i32 m0, s52, 0x1c000
	v_lshl_add_u64 v[4:5], s[28:29], 0, v[2:3]
	global_load_lds_dwordx4 v[4:5], off
	v_lshl_add_u64 v[4:5], s[28:29], 0, v[136:137]
	s_add_i32 m0, s52, 0x1e000
	s_cmpk_lt_u32 s26, 0x100
	global_load_lds_dwordx4 v[4:5], off
	v_lshrrev_b32_e32 v5, 1, v12
	v_and_b32_e32 v5, 24, v5
	v_and_b32_e32 v4, 15, v12
	v_lshlrev_b32_e32 v6, 1, v5
	v_lshl_or_b32 v1, s27, 6, v4
	v_lshl_or_b32 v4, v4, 6, v6
	v_lshlrev_b32_e32 v6, 2, v12
	v_and_b32_e32 v6, 32, v6
	v_bitop3_b32 v7, v4, s30, v6 bitop3:0xde
	v_bitop3_b32 v147, v4, s42, v6 bitop3:0xde
	v_lshlrev_b32_e32 v4, 14, v17
	v_and_b32_e32 v4, 0xffff8000, v4
	v_or_b32_e32 v149, s31, v5
	v_lshl_add_u32 v4, v16, 11, v4
	v_and_b32_e32 v5, 1, v17
	v_lshl_or_b32 v4, v5, 6, v4
	v_lshl_add_u32 v142, v18, 1, v4
	v_lshlrev_b32_e32 v4, 14, v13
	v_and_b32_e32 v4, 0xffff8000, v4
	s_waitcnt vmcnt(6)
	v_lshl_add_u32 v4, v14, 11, v4
	v_and_b32_e32 v5, 1, v13
	v_lshl_or_b32 v4, v5, 6, v4
	v_readlane_b32 s28, v254, 26
	s_cselect_b64 s[26:27], -1, 0
	v_mov_b32_e32 v143, v3
	v_lshl_add_u32 v144, v15, 1, v4
	v_mov_b32_e32 v145, v3
	s_mov_b32 s57, 0
	s_mov_b32 s72, -1
	v_add_u32_e32 v151, 0, v7
	v_readlane_b32 s58, v254, 14
	s_mov_b32 s59, s28
	s_barrier
	v_readlane_b32 s29, v254, 27
	s_branch .LBB0_860

.LBB0_866:
	v_lshl_add_u32 v176, s59, 8, v1
	v_ashrrev_i32_e32 v177, 31, v176
	v_lshlrev_b32_e32 v250, 2, v0
	v_add_u32_e32 v250, 0x20000, v250
	s_cmp_eq_u32 s59, s72
	s_cbranch_scc1 .Lsg_cached
	v_lshl_add_u64 v[132:133], v[176:177], 4, s[24:25]
	v_mov_b64_e32 v[192:193], v[132:133]
	global_load_dwordx4 v[132:135], v[132:133], off
	global_load_dwordx4 v[188:191], v[192:193], off offset:256
	global_load_dwordx4 v[210:213], v[192:193], off offset:512
	global_load_dwordx4 v[234:237], v[192:193], off offset:768
	global_load_dwordx4 v[238:241], v[192:193], off offset:2048
	global_load_dwordx4 v[242:245], v[192:193], off offset:2304
	global_load_dwordx4 v[246:249], v[192:193], off offset:2560
	s_mov_b32 s18, 0xf800000
	v_or_b32_e32 v166, 16, v176
	v_ashrrev_i32_e32 v167, 31, v166
	v_or_b32_e32 v162, 32, v176
	v_ashrrev_i32_e32 v163, 31, v162
	v_or_b32_e32 v156, 48, v176
	v_ashrrev_i32_e32 v157, 31, v156
	v_add_u32_e32 v178, 0x90, v176
	v_ashrrev_i32_e32 v179, 31, v178
	v_add_u32_e32 v180, 0xa0, v176
	v_ashrrev_i32_e32 v181, 31, v180
	v_add_u32_e32 v182, 0xb0, v176
	v_ashrrev_i32_e32 v183, 31, v182
	v_mov_b32_e32 v186, v120
	v_mov_b32_e32 v187, v128
	v_mov_b32_e32 v128, v121
	s_waitcnt vmcnt(6)
	v_mov_b32_e32 v152, v133
	v_mov_b32_e32 v153, v134
	v_mov_b32_e32 v133, v135
	v_pk_add_f32 v[132:133], v[152:153], v[132:133]
	s_nop 0
	v_add_f32_e32 v132, v132, v133
	v_fmamk_f32 v132, v132, 0x3a800000, v215
	v_cmp_gt_f32_e32 vcc, s18, v132
	v_mul_f32_e32 v133, 0x4f800000, v132
	s_nop 0
	v_cndmask_b32_e32 v132, v132, v133, vcc
	v_sqrt_f32_e32 v133, v132
	s_nop 0
	v_add_u32_e32 v134, -1, v133
	v_fma_f32 v135, -v134, v133, v132
	v_cmp_ge_f32_e64 s[4:5], 0, v135
	v_add_u32_e32 v135, 1, v133
	s_nop 0
	v_cndmask_b32_e64 v134, v133, v134, s[4:5]
	v_fma_f32 v133, -v135, v133, v132
	v_cmp_lt_f32_e64 s[4:5], 0, v133
	s_nop 1
	v_cndmask_b32_e64 v133, v134, v135, s[4:5]
	v_mul_f32_e32 v134, 0x37800000, v133
	v_cndmask_b32_e32 v133, v133, v134, vcc
	v_cmp_class_f32_e32 vcc, v132, v216
	s_nop 1
	v_cndmask_b32_e32 v132, v133, v132, vcc
	v_div_scale_f32 v133, s[4:5], v132, v132, 1.0
	v_rcp_f32_e32 v134, v133
	s_nop 0
	v_fma_f32 v135, -v133, v134, 1.0
	v_fmac_f32_e32 v134, v135, v134
	v_div_scale_f32 v135, vcc, 1.0, v132, 1.0
	v_mul_f32_e32 v146, v135, v134
	v_fma_f32 v148, -v133, v146, v135
	v_fmac_f32_e32 v146, v148, v134
	v_fma_f32 v133, -v133, v146, v135
	v_div_fmas_f32 v133, v133, v134, v146
	v_div_fixup_f32 v158, v133, v132, 1.0
	v_lshl_add_u64 v[132:133], v[166:167], 4, s[24:25]
	v_pk_mul_f32 v[186:187], v[186:187], v[158:159] op_sel_hi:[1,0]
	s_waitcnt vmcnt(5)
	v_mov_b64_e32 v[132:133], v[188:189]
	v_mov_b64_e32 v[134:135], v[190:191]
	global_load_dwordx4 v[188:191], v[192:193], off offset:2816
	v_mov_b32_e32 v152, v133
	v_mov_b32_e32 v153, v134
	v_mov_b32_e32 v133, v135
	v_pk_add_f32 v[132:133], v[152:153], v[132:133]
	v_mul_f32_e32 v120, 0xbfb8aa3b, v187
	v_add_f32_e32 v132, v132, v133
	v_fmamk_f32 v132, v132, 0x3a800000, v215
	v_cmp_gt_f32_e32 vcc, s18, v132
	v_mul_f32_e32 v133, 0x4f800000, v132
	v_exp_f32_e32 v120, v120
	v_cndmask_b32_e32 v132, v132, v133, vcc
	v_sqrt_f32_e32 v133, v132
	v_add_f32_e32 v120, 1.0, v120
	v_rcp_f32_e32 v120, v120
	v_add_u32_e32 v134, -1, v133
	v_fma_f32 v135, -v134, v133, v132
	v_cmp_ge_f32_e64 s[4:5], 0, v135
	v_add_u32_e32 v135, 1, v133
	v_mul_f32_e32 v120, v187, v120
	v_cndmask_b32_e64 v134, v133, v134, s[4:5]
	v_fma_f32 v133, -v135, v133, v132
	v_cmp_lt_f32_e64 s[4:5], 0, v133
	v_mov_b32_e32 v187, v124
	v_mov_b32_e32 v124, v117
	v_cndmask_b32_e64 v133, v134, v135, s[4:5]
	v_mul_f32_e32 v134, 0x37800000, v133
	v_cndmask_b32_e32 v133, v133, v134, vcc
	v_cmp_class_f32_e32 vcc, v132, v216
	s_nop 1
	v_cndmask_b32_e32 v132, v133, v132, vcc
	v_div_scale_f32 v133, s[4:5], v132, v132, 1.0
	v_rcp_f32_e32 v134, v133
	s_nop 0
	v_fma_f32 v135, -v133, v134, 1.0
	v_fmac_f32_e32 v134, v135, v134
	v_div_scale_f32 v135, vcc, 1.0, v132, 1.0
	v_mul_f32_e32 v146, v135, v134
	v_fma_f32 v148, -v133, v146, v135
	v_fmac_f32_e32 v146, v148, v134
	v_fma_f32 v133, -v133, v146, v135
	v_div_fmas_f32 v133, v133, v134, v146
	v_div_fixup_f32 v154, v133, v132, 1.0
	v_lshl_add_u64 v[132:133], v[162:163], 4, s[24:25]
	s_waitcnt vmcnt(5)
	v_mov_b64_e32 v[132:133], v[210:211]
	v_mov_b64_e32 v[134:135], v[212:213]
	v_mov_b32_e32 v152, v133
	v_mov_b32_e32 v153, v134
	v_mov_b32_e32 v133, v135
	v_pk_add_f32 v[132:133], v[152:153], v[132:133]
	s_nop 0
	v_add_f32_e32 v132, v132, v133
	v_fmamk_f32 v132, v132, 0x3a800000, v215
	v_cmp_gt_f32_e32 vcc, s18, v132
	v_mul_f32_e32 v133, 0x4f800000, v132
	s_nop 0
	v_cndmask_b32_e32 v132, v132, v133, vcc
	v_sqrt_f32_e32 v133, v132
	s_nop 0
	v_add_u32_e32 v134, -1, v133
	v_fma_f32 v135, -v134, v133, v132
	v_cmp_ge_f32_e64 s[4:5], 0, v135
	v_add_u32_e32 v135, 1, v133
	s_nop 0
	v_cndmask_b32_e64 v134, v133, v134, s[4:5]
	v_fma_f32 v133, -v135, v133, v132
	v_cmp_lt_f32_e64 s[4:5], 0, v133
	s_nop 1
	v_cndmask_b32_e64 v133, v134, v135, s[4:5]
	v_mul_f32_e32 v134, 0x37800000, v133
	v_cndmask_b32_e32 v133, v133, v134, vcc
	v_cmp_class_f32_e32 vcc, v132, v216
	s_nop 1
	v_cndmask_b32_e32 v132, v133, v132, vcc
	v_div_scale_f32 v133, s[4:5], v132, v132, 1.0
	v_rcp_f32_e32 v134, v133
	s_nop 0
	v_fma_f32 v135, -v133, v134, 1.0
	v_fmac_f32_e32 v134, v135, v134
	v_div_scale_f32 v135, vcc, 1.0, v132, 1.0
	v_mul_f32_e32 v146, v135, v134
	v_fma_f32 v148, -v133, v146, v135
	v_fmac_f32_e32 v146, v148, v134
	v_fma_f32 v133, -v133, v146, v135
	v_div_fmas_f32 v133, v133, v134, v146
	v_div_fixup_f32 v150, v133, v132, 1.0
	v_lshl_add_u64 v[132:133], v[156:157], 4, s[24:25]
	s_waitcnt vmcnt(4)
	v_mov_b64_e32 v[132:133], v[234:235]
	v_mov_b64_e32 v[134:135], v[236:237]
	v_mov_b32_e32 v152, v133
	v_mov_b32_e32 v153, v134
	v_mov_b32_e32 v133, v135
	v_pk_add_f32 v[132:133], v[152:153], v[132:133]
	v_add_u32_e32 v152, 0x80, v176
	v_add_f32_e32 v132, v132, v133
	v_fmamk_f32 v132, v132, 0x3a800000, v215
	v_cmp_gt_f32_e32 vcc, s18, v132
	v_mul_f32_e32 v133, 0x4f800000, v132
	v_ashrrev_i32_e32 v153, 31, v152
	v_cndmask_b32_e32 v132, v132, v133, vcc
	v_sqrt_f32_e32 v133, v132
	s_nop 0
	v_add_u32_e32 v134, -1, v133
	v_fma_f32 v135, -v134, v133, v132
	v_cmp_ge_f32_e64 s[4:5], 0, v135
	v_add_u32_e32 v135, 1, v133
	s_nop 0
	v_cndmask_b32_e64 v134, v133, v134, s[4:5]
	v_fma_f32 v133, -v135, v133, v132
	v_cmp_lt_f32_e64 s[4:5], 0, v133
	s_nop 1
	v_cndmask_b32_e64 v133, v134, v135, s[4:5]
	v_mul_f32_e32 v134, 0x37800000, v133
	v_cndmask_b32_e32 v133, v133, v134, vcc
	v_cmp_class_f32_e32 vcc, v132, v216
	s_nop 1
	v_cndmask_b32_e32 v132, v133, v132, vcc
	v_div_scale_f32 v133, s[4:5], v132, v132, 1.0
	v_rcp_f32_e32 v134, v133
	s_nop 0
	v_fma_f32 v135, -v133, v134, 1.0
	v_fmac_f32_e32 v134, v135, v134
	v_div_scale_f32 v135, vcc, 1.0, v132, 1.0
	v_mul_f32_e32 v146, v135, v134
	v_fma_f32 v148, -v133, v146, v135
	v_fmac_f32_e32 v146, v148, v134
	v_fma_f32 v133, -v133, v146, v135
	v_div_fmas_f32 v133, v133, v134, v146
	v_div_fixup_f32 v148, v133, v132, 1.0
	v_lshl_add_u64 v[132:133], v[152:153], 4, s[24:25]
	s_waitcnt vmcnt(3)
	v_mov_b64_e32 v[132:133], v[238:239]
	v_mov_b64_e32 v[134:135], v[240:241]
	v_mov_b32_e32 v160, v133
	v_mov_b32_e32 v161, v134
	v_mov_b32_e32 v133, v135
	v_pk_add_f32 v[132:133], v[160:161], v[132:133]
	s_nop 0
	v_add_f32_e32 v132, v132, v133
	v_fmamk_f32 v132, v132, 0x3a800000, v215
	v_cmp_gt_f32_e32 vcc, s18, v132
	v_mul_f32_e32 v133, 0x4f800000, v132
	s_nop 0
	v_cndmask_b32_e32 v132, v132, v133, vcc
	v_sqrt_f32_e32 v133, v132
	s_nop 0
	v_add_u32_e32 v134, -1, v133
	v_fma_f32 v135, -v134, v133, v132
	v_cmp_ge_f32_e64 s[4:5], 0, v135
	v_add_u32_e32 v135, 1, v133
	s_nop 0
	v_cndmask_b32_e64 v134, v133, v134, s[4:5]
	v_fma_f32 v133, -v135, v133, v132
	v_cmp_lt_f32_e64 s[4:5], 0, v133
	s_nop 1
	v_cndmask_b32_e64 v133, v134, v135, s[4:5]
	v_mul_f32_e32 v134, 0x37800000, v133
	v_cndmask_b32_e32 v133, v133, v134, vcc
	v_cmp_class_f32_e32 vcc, v132, v216
	s_nop 1
	v_cndmask_b32_e32 v132, v133, v132, vcc
	v_div_scale_f32 v133, s[4:5], v132, v132, 1.0
	v_rcp_f32_e32 v134, v133
	s_nop 0
	v_fma_f32 v135, -v133, v134, 1.0
	v_fmac_f32_e32 v134, v135, v134
	v_div_scale_f32 v135, vcc, 1.0, v132, 1.0
	v_mul_f32_e32 v146, v135, v134
	v_fma_f32 v153, -v133, v146, v135
	v_fmac_f32_e32 v146, v153, v134
	v_fma_f32 v133, -v133, v146, v135
	v_div_fmas_f32 v133, v133, v134, v146
	v_div_fixup_f32 v146, v133, v132, 1.0
	v_lshl_add_u64 v[132:133], v[178:179], 4, s[24:25]
	s_waitcnt vmcnt(2)
	v_mov_b64_e32 v[132:133], v[242:243]
	v_mov_b64_e32 v[134:135], v[244:245]
	v_mov_b32_e32 v160, v133
	v_mov_b32_e32 v161, v134
	v_mov_b32_e32 v133, v135
	v_pk_add_f32 v[132:133], v[160:161], v[132:133]
	s_nop 0
	v_add_f32_e32 v132, v132, v133
	v_fmamk_f32 v132, v132, 0x3a800000, v215
	v_cmp_gt_f32_e32 vcc, s18, v132
	v_mul_f32_e32 v133, 0x4f800000, v132
	s_nop 0
	v_cndmask_b32_e32 v132, v132, v133, vcc
	v_sqrt_f32_e32 v133, v132
	s_nop 0
	v_add_u32_e32 v134, -1, v133
	v_fma_f32 v135, -v134, v133, v132
	v_cmp_ge_f32_e64 s[4:5], 0, v135
	v_add_u32_e32 v135, 1, v133
	s_nop 0
	v_cndmask_b32_e64 v134, v133, v134, s[4:5]
	v_fma_f32 v133, -v135, v133, v132
	v_cmp_lt_f32_e64 s[4:5], 0, v133
	s_nop 1
	v_cndmask_b32_e64 v133, v134, v135, s[4:5]
	v_mul_f32_e32 v134, 0x37800000, v133
	v_cndmask_b32_e32 v133, v133, v134, vcc
	v_cmp_class_f32_e32 vcc, v132, v216
	s_nop 1
	v_cndmask_b32_e32 v132, v133, v132, vcc
	v_div_scale_f32 v133, s[4:5], v132, v132, 1.0
	v_rcp_f32_e32 v134, v133
	s_nop 0
	v_fma_f32 v135, -v133, v134, 1.0
	v_fmac_f32_e32 v134, v135, v134
	v_div_scale_f32 v135, vcc, 1.0, v132, 1.0
	v_mul_f32_e32 v153, v135, v134
	v_fma_f32 v155, -v133, v153, v135
	v_fmac_f32_e32 v153, v155, v134
	v_fma_f32 v133, -v133, v153, v135
	v_div_fmas_f32 v133, v133, v134, v153
	v_div_fixup_f32 v160, v133, v132, 1.0
	v_lshl_add_u64 v[132:133], v[180:181], 4, s[24:25]
	s_waitcnt vmcnt(1)
	v_mov_b64_e32 v[132:133], v[246:247]
	v_mov_b64_e32 v[134:135], v[248:249]
	v_mov_b32_e32 v164, v133
	v_mov_b32_e32 v165, v134
	v_mov_b32_e32 v133, v135
	v_pk_add_f32 v[132:133], v[164:165], v[132:133]
	s_nop 0
	v_add_f32_e32 v132, v132, v133
	v_fmamk_f32 v132, v132, 0x3a800000, v215
	v_cmp_gt_f32_e32 vcc, s18, v132
	v_mul_f32_e32 v133, 0x4f800000, v132
	s_nop 0
	v_cndmask_b32_e32 v132, v132, v133, vcc
	v_sqrt_f32_e32 v133, v132
	s_nop 0
	v_add_u32_e32 v134, -1, v133
	v_fma_f32 v135, -v134, v133, v132
	v_cmp_ge_f32_e64 s[4:5], 0, v135
	v_add_u32_e32 v135, 1, v133
	s_nop 0
	v_cndmask_b32_e64 v134, v133, v134, s[4:5]
	v_fma_f32 v133, -v135, v133, v132
	v_cmp_lt_f32_e64 s[4:5], 0, v133
	s_nop 1
	v_cndmask_b32_e64 v133, v134, v135, s[4:5]
	v_mul_f32_e32 v134, 0x37800000, v133
	v_cndmask_b32_e32 v133, v133, v134, vcc
	v_cmp_class_f32_e32 vcc, v132, v216
	s_nop 1
	v_cndmask_b32_e32 v132, v133, v132, vcc
	v_div_scale_f32 v133, s[4:5], v132, v132, 1.0
	v_rcp_f32_e32 v134, v133
	s_nop 0
	v_fma_f32 v135, -v133, v134, 1.0
	v_fmac_f32_e32 v134, v135, v134
	v_div_scale_f32 v135, vcc, 1.0, v132, 1.0
	v_mul_f32_e32 v153, v135, v134
	v_fma_f32 v155, -v133, v153, v135
	v_fmac_f32_e32 v153, v155, v134
	v_fma_f32 v133, -v133, v153, v135
	v_div_fmas_f32 v133, v133, v134, v153
	v_div_fixup_f32 v164, v133, v132, 1.0
	v_lshl_add_u64 v[132:133], v[182:183], 4, s[24:25]
	s_waitcnt vmcnt(0)
	v_mov_b64_e32 v[132:133], v[188:189]
	v_mov_b64_e32 v[134:135], v[190:191]
	v_mov_b32_e32 v184, v133
	v_mov_b32_e32 v185, v134
	v_mov_b32_e32 v133, v135
	v_pk_add_f32 v[132:133], v[184:185], v[132:133]
	v_lshl_or_b32 v184, s58, 7, v149
	v_add_f32_e32 v132, v132, v133
	v_fmamk_f32 v132, v132, 0x3a800000, v215
	v_cmp_gt_f32_e32 vcc, s18, v132
	v_mul_f32_e32 v133, 0x4f800000, v132
	v_ashrrev_i32_e32 v185, 31, v184
	v_cndmask_b32_e32 v132, v132, v133, vcc
	v_sqrt_f32_e32 v133, v132
	s_movk_i32 s18, 0x1600
	v_add_u32_e32 v134, -1, v133
	v_fma_f32 v135, -v134, v133, v132
	v_cmp_ge_f32_e64 s[4:5], 0, v135
	v_add_u32_e32 v135, 1, v133
	s_nop 0
	v_cndmask_b32_e64 v134, v133, v134, s[4:5]
	v_fma_f32 v133, -v135, v133, v132
	v_cmp_lt_f32_e64 s[4:5], 0, v133
	s_nop 1
	v_cndmask_b32_e64 v133, v134, v135, s[4:5]
	v_mul_f32_e32 v134, 0x37800000, v133
	v_cndmask_b32_e32 v133, v133, v134, vcc
	v_cmp_class_f32_e32 vcc, v132, v216
	s_nop 1
	v_cndmask_b32_e32 v132, v133, v132, vcc
	v_div_scale_f32 v133, s[4:5], v132, v132, 1.0
	v_rcp_f32_e32 v134, v133
	s_nop 0
	v_fma_f32 v135, -v133, v134, 1.0
	v_fmac_f32_e32 v134, v135, v134
	v_div_scale_f32 v135, vcc, 1.0, v132, 1.0
	v_mul_f32_e32 v153, v135, v134
	v_fma_f32 v155, -v133, v153, v135
	v_fmac_f32_e32 v153, v155, v134
	v_fma_f32 v133, -v133, v153, v135
	v_div_fmas_f32 v133, v133, v134, v153
	v_div_fixup_f32 v132, v133, v132, 1.0
	ds_write_b32 v250, v158
	ds_write_b32 v250, v154 offset:2048
	ds_write_b32 v250, v150 offset:4096
	ds_write_b32 v250, v148 offset:6144
	ds_write_b32 v250, v146 offset:8192
	ds_write_b32 v250, v160 offset:10240
	ds_write_b32 v250, v164 offset:12288
	ds_write_b32 v250, v132 offset:14336
	s_mov_b32 s72, s59
	s_branch .Lsg_join
.Lsg_cached:
	ds_read_b32 v158, v250
	ds_read_b32 v154, v250 offset:2048
	ds_read_b32 v150, v250 offset:4096
	ds_read_b32 v148, v250 offset:6144
	ds_read_b32 v146, v250 offset:8192
	ds_read_b32 v160, v250 offset:10240
	ds_read_b32 v164, v250 offset:12288
	ds_read_b32 v132, v250 offset:14336
	v_or_b32_e32 v166, 16, v176
	v_or_b32_e32 v162, 32, v176
	v_or_b32_e32 v156, 48, v176
	v_add_u32_e32 v178, 0x90, v176
	v_add_u32_e32 v180, 0xa0, v176
	v_add_u32_e32 v182, 0xb0, v176
	v_add_u32_e32 v152, 0x80, v176
	v_lshl_or_b32 v184, s58, 7, v149
	v_ashrrev_i32_e32 v185, 31, v184
	s_movk_i32 s18, 0x1600
	v_mov_b32_e32 v186, v120
	v_mov_b32_e32 v187, v128
	v_mov_b32_e32 v128, v121
	s_waitcnt lgkmcnt(7)
	v_pk_mul_f32 v[186:187], v[186:187], v[158:159] op_sel_hi:[1,0]
	s_nop 0
	v_mul_f32_e32 v120, 0xbfb8aa3b, v187
	v_exp_f32_e32 v120, v120
	s_nop 0
	v_add_f32_e32 v120, 1.0, v120
	v_rcp_f32_e32 v120, v120
	s_nop 0
	v_mul_f32_e32 v120, v187, v120
	v_mov_b32_e32 v187, v124
	v_mov_b32_e32 v124, v117
	s_waitcnt lgkmcnt(0)
.Lsg_join:
	v_mul_f32_e32 v133, v186, v120
	v_mov_b32_e32 v186, v116
	v_pk_mul_f32 v[186:187], v[186:187], v[158:159] op_sel_hi:[1,0]
	v_pk_mul_f32 v[120:121], v[128:129], v[158:159] op_sel_hi:[1,0]
	v_mul_f32_e32 v116, 0xbfb8aa3b, v187
	v_exp_f32_e32 v116, v116
	v_mov_b64_e32 v[134:135], s[22:23]
	v_mad_i64_i32 v[176:177], s[4:5], v176, s18, v[134:135]
	v_add_f32_e32 v116, 1.0, v116
	v_rcp_f32_e32 v116, v116
	s_andn2_b64 vcc, exec, s[42:43]
	v_mul_f32_e32 v116, v187, v116
	v_mul_f32_e32 v153, v186, v116
	v_mul_f32_e32 v116, 0xbfb8aa3b, v121
	v_exp_f32_e32 v116, v116
	s_nop 0
	v_add_f32_e32 v116, 1.0, v116
	v_rcp_f32_e32 v116, v116
	s_nop 0
	v_mul_f32_e32 v116, v121, v116
	v_mul_f32_e32 v120, v120, v116
	v_pk_mul_f32 v[116:117], v[124:125], v[158:159] op_sel_hi:[1,0]
	s_nop 0
	v_mul_f32_e32 v121, 0xbfb8aa3b, v117
	v_exp_f32_e32 v121, v121
	s_nop 0
	v_add_f32_e32 v121, 1.0, v121
	v_rcp_f32_e32 v121, v121
	s_nop 0
	v_mul_f32_e32 v117, v117, v121
	v_mul_f32_e32 v121, v116, v117
	v_mov_b32_e32 v116, v122
	v_mov_b32_e32 v117, v130
	v_pk_mul_f32 v[116:117], v[116:117], v[158:159] op_sel_hi:[1,0]
	v_mov_b32_e32 v130, v123
	v_mul_f32_e32 v122, 0xbfb8aa3b, v117
	v_exp_f32_e32 v122, v122
	s_nop 0
	v_add_f32_e32 v122, 1.0, v122
	v_rcp_f32_e32 v122, v122
	s_nop 0
	v_mul_f32_e32 v117, v117, v122
	v_mul_f32_e32 v124, v116, v117
	v_mov_b32_e32 v116, v118
	v_mov_b32_e32 v117, v126
	v_pk_mul_f32 v[116:117], v[116:117], v[158:159] op_sel_hi:[1,0]
	v_mov_b32_e32 v126, v119
	v_mul_f32_e32 v118, 0xbfb8aa3b, v117
	v_exp_f32_e32 v118, v118
	s_nop 0
	v_add_f32_e32 v118, 1.0, v118
	v_rcp_f32_e32 v118, v118
	s_nop 0
	v_mul_f32_e32 v117, v117, v118
	v_mul_f32_e32 v125, v116, v117
	v_pk_mul_f32 v[116:117], v[130:131], v[158:159] op_sel_hi:[1,0]
	s_nop 0
	v_mul_f32_e32 v118, 0xbfb8aa3b, v117
	v_exp_f32_e32 v118, v118
	s_nop 0
	v_add_f32_e32 v118, 1.0, v118
	v_rcp_f32_e32 v118, v118
	s_nop 0
	v_mul_f32_e32 v117, v117, v118
	v_mul_f32_e32 v128, v116, v117
	v_pk_mul_f32 v[116:117], v[126:127], v[158:159] op_sel_hi:[1,0]
	s_nop 0
	v_mul_f32_e32 v118, 0xbfb8aa3b, v117
	v_exp_f32_e32 v118, v118
	s_nop 0
	v_add_f32_e32 v118, 1.0, v118
	v_rcp_f32_e32 v118, v118
	s_nop 0
	v_mul_f32_e32 v117, v117, v118
	v_mul_f32_e32 v126, v116, v117
	v_lshlrev_b64 v[116:117], 1, v[184:185]
	v_lshl_add_u64 v[122:123], v[176:177], 0, v[116:117]
	v_cvt_pk_bf16_f32 v118, v133, v120
	v_cvt_pk_bf16_f32 v119, v124, v128
	v_cvt_pk_bf16_f32 v120, v153, v121
	v_cvt_pk_bf16_f32 v121, v125, v126
	global_store_dwordx4 v[122:123], v[118:121], off
	s_nop 1
	v_mov_b32_e32 v120, v104
	v_mov_b32_e32 v121, v112
	v_pk_mul_f32 v[120:121], v[120:121], v[154:155] op_sel_hi:[1,0]
	v_mov_b32_e32 v112, v105
	v_mul_f32_e32 v104, 0xbfb8aa3b, v121
	v_exp_f32_e32 v104, v104
	v_mad_i64_i32 v[118:119], s[4:5], v166, s18, v[134:135]
	v_add_f32_e32 v104, 1.0, v104
	v_rcp_f32_e32 v104, v104
	s_nop 0
	v_mul_f32_e32 v104, v121, v104
	v_mul_f32_e32 v122, v120, v104
	v_mov_b32_e32 v120, v100
	v_mov_b32_e32 v121, v108
	v_pk_mul_f32 v[120:121], v[120:121], v[154:155] op_sel_hi:[1,0]
	v_pk_mul_f32 v[104:105], v[112:113], v[154:155] op_sel_hi:[1,0]
	v_mul_f32_e32 v100, 0xbfb8aa3b, v121
	v_exp_f32_e32 v100, v100
	v_mov_b32_e32 v108, v101
	v_add_f32_e32 v100, 1.0, v100
	v_rcp_f32_e32 v100, v100
	s_nop 0
	v_mul_f32_e32 v100, v121, v100
	v_mul_f32_e32 v120, v120, v100
	v_mul_f32_e32 v100, 0xbfb8aa3b, v105
	v_exp_f32_e32 v100, v100
	s_nop 0
	v_add_f32_e32 v100, 1.0, v100
	v_rcp_f32_e32 v100, v100
	s_nop 0
	v_mul_f32_e32 v100, v105, v100
	v_mul_f32_e32 v112, v104, v100
	v_pk_mul_f32 v[100:101], v[108:109], v[154:155] op_sel_hi:[1,0]
	s_nop 0
	v_mul_f32_e32 v104, 0xbfb8aa3b, v101
	v_exp_f32_e32 v104, v104
	s_nop 0
	v_add_f32_e32 v104, 1.0, v104
	v_rcp_f32_e32 v104, v104
	s_nop 0
	v_mul_f32_e32 v101, v101, v104
	v_mul_f32_e32 v108, v100, v101
	v_mov_b32_e32 v100, v106
	v_mov_b32_e32 v101, v114
	v_pk_mul_f32 v[100:101], v[100:101], v[154:155] op_sel_hi:[1,0]
	v_mov_b32_e32 v114, v107
	v_mul_f32_e32 v104, 0xbfb8aa3b, v101
	v_exp_f32_e32 v104, v104
	s_nop 0
	v_add_f32_e32 v104, 1.0, v104
	v_rcp_f32_e32 v104, v104
	s_nop 0
	v_mul_f32_e32 v101, v101, v104
	v_mul_f32_e32 v106, v100, v101
	v_mov_b32_e32 v100, v102
	v_mov_b32_e32 v101, v110
	v_pk_mul_f32 v[100:101], v[100:101], v[154:155] op_sel_hi:[1,0]
	v_mov_b32_e32 v110, v103
	v_mul_f32_e32 v102, 0xbfb8aa3b, v101
	v_exp_f32_e32 v102, v102
	v_lshl_add_u64 v[104:105], v[118:119], 0, v[116:117]
	v_add_f32_e32 v102, 1.0, v102
	v_rcp_f32_e32 v102, v102
	s_nop 0
	v_mul_f32_e32 v101, v101, v102
	v_mul_f32_e32 v109, v100, v101
	v_pk_mul_f32 v[100:101], v[114:115], v[154:155] op_sel_hi:[1,0]
	s_nop 0
	v_mul_f32_e32 v102, 0xbfb8aa3b, v101
	v_exp_f32_e32 v102, v102
	s_nop 0
	v_add_f32_e32 v102, 1.0, v102
	v_rcp_f32_e32 v102, v102
	s_nop 0
	v_mul_f32_e32 v101, v101, v102
	v_mul_f32_e32 v102, v100, v101
	v_pk_mul_f32 v[100:101], v[110:111], v[154:155] op_sel_hi:[1,0]
	s_nop 0
	v_mul_f32_e32 v103, 0xbfb8aa3b, v101
	v_exp_f32_e32 v103, v103
	s_nop 0
	v_add_f32_e32 v103, 1.0, v103
	v_rcp_f32_e32 v103, v103
	s_nop 0
	v_mul_f32_e32 v101, v101, v103
	v_mul_f32_e32 v103, v100, v101
	v_cvt_pk_bf16_f32 v100, v122, v112
	v_cvt_pk_bf16_f32 v101, v106, v102
	v_cvt_pk_bf16_f32 v102, v120, v108
	v_cvt_pk_bf16_f32 v103, v109, v103
	global_store_dwordx4 v[104:105], v[100:103], off
	s_nop 1
	v_mov_b32_e32 v102, v88
	v_mov_b32_e32 v103, v96
	v_pk_mul_f32 v[102:103], v[102:103], v[150:151] op_sel_hi:[1,0]
	v_mov_b32_e32 v96, v89
	v_mul_f32_e32 v88, 0xbfb8aa3b, v103
	v_exp_f32_e32 v88, v88
	v_mad_i64_i32 v[100:101], s[4:5], v162, s18, v[134:135]
	v_add_f32_e32 v88, 1.0, v88
	v_rcp_f32_e32 v88, v88
	s_nop 0
	v_mul_f32_e32 v88, v103, v88
	v_mul_f32_e32 v104, v102, v88
	v_mov_b32_e32 v102, v84
	v_mov_b32_e32 v103, v92
	v_pk_mul_f32 v[102:103], v[102:103], v[150:151] op_sel_hi:[1,0]
	v_pk_mul_f32 v[88:89], v[96:97], v[150:151] op_sel_hi:[1,0]
	v_mul_f32_e32 v84, 0xbfb8aa3b, v103
	v_exp_f32_e32 v84, v84
	v_mov_b32_e32 v92, v85
	v_add_f32_e32 v84, 1.0, v84
	v_rcp_f32_e32 v84, v84
	s_nop 0
	v_mul_f32_e32 v84, v103, v84
	v_mul_f32_e32 v102, v102, v84
	v_mul_f32_e32 v84, 0xbfb8aa3b, v89
	v_exp_f32_e32 v84, v84
	s_nop 0
	v_add_f32_e32 v84, 1.0, v84
	v_rcp_f32_e32 v84, v84
	s_nop 0
	v_mul_f32_e32 v84, v89, v84
	v_mul_f32_e32 v96, v88, v84
	v_pk_mul_f32 v[84:85], v[92:93], v[150:151] op_sel_hi:[1,0]
	s_nop 0
	v_mul_f32_e32 v88, 0xbfb8aa3b, v85
	v_exp_f32_e32 v88, v88
	s_nop 0
	v_add_f32_e32 v88, 1.0, v88
	v_rcp_f32_e32 v88, v88
	s_nop 0
	v_mul_f32_e32 v85, v85, v88
	v_mul_f32_e32 v92, v84, v85
	v_mov_b32_e32 v84, v90
	v_mov_b32_e32 v85, v98
	v_pk_mul_f32 v[84:85], v[84:85], v[150:151] op_sel_hi:[1,0]
	v_mov_b32_e32 v98, v91
	v_mul_f32_e32 v88, 0xbfb8aa3b, v85
	v_exp_f32_e32 v88, v88
	s_nop 0
	v_add_f32_e32 v88, 1.0, v88
	v_rcp_f32_e32 v88, v88
	s_nop 0
	v_mul_f32_e32 v85, v85, v88
	v_mul_f32_e32 v90, v84, v85
	v_mov_b32_e32 v84, v86
	v_mov_b32_e32 v85, v94
	v_pk_mul_f32 v[84:85], v[84:85], v[150:151] op_sel_hi:[1,0]
	v_mov_b32_e32 v94, v87
	v_mul_f32_e32 v86, 0xbfb8aa3b, v85
	v_exp_f32_e32 v86, v86
	v_lshl_add_u64 v[88:89], v[100:101], 0, v[116:117]
	v_add_f32_e32 v86, 1.0, v86
	v_rcp_f32_e32 v86, v86
	s_nop 0
	v_mul_f32_e32 v85, v85, v86
	v_mul_f32_e32 v93, v84, v85
	v_pk_mul_f32 v[84:85], v[98:99], v[150:151] op_sel_hi:[1,0]
	s_nop 0
	v_mul_f32_e32 v86, 0xbfb8aa3b, v85
	v_exp_f32_e32 v86, v86
	s_nop 0
	v_add_f32_e32 v86, 1.0, v86
	v_rcp_f32_e32 v86, v86
	s_nop 0
	v_mul_f32_e32 v85, v85, v86
	v_mul_f32_e32 v86, v84, v85
	v_pk_mul_f32 v[84:85], v[94:95], v[150:151] op_sel_hi:[1,0]
	s_nop 0
	v_mul_f32_e32 v87, 0xbfb8aa3b, v85
	v_exp_f32_e32 v87, v87
	s_nop 0
	v_add_f32_e32 v87, 1.0, v87
	v_rcp_f32_e32 v87, v87
	s_nop 0
	v_mul_f32_e32 v85, v85, v87
	v_mul_f32_e32 v87, v84, v85
	v_cvt_pk_bf16_f32 v84, v104, v96
	v_cvt_pk_bf16_f32 v85, v90, v86
	v_cvt_pk_bf16_f32 v86, v102, v92
	v_cvt_pk_bf16_f32 v87, v93, v87
	global_store_dwordx4 v[88:89], v[84:87], off
	s_nop 1
	v_mov_b32_e32 v86, v72
	v_mov_b32_e32 v87, v80
	v_pk_mul_f32 v[86:87], v[86:87], v[148:149] op_sel_hi:[1,0]
	v_mov_b32_e32 v80, v73
	v_mul_f32_e32 v72, 0xbfb8aa3b, v87
	v_exp_f32_e32 v72, v72
	v_mad_i64_i32 v[84:85], s[4:5], v156, s18, v[134:135]
	v_add_f32_e32 v72, 1.0, v72
	v_rcp_f32_e32 v72, v72
	s_nop 0
	v_mul_f32_e32 v72, v87, v72
	v_mul_f32_e32 v88, v86, v72
	v_mov_b32_e32 v86, v68
	v_mov_b32_e32 v87, v76
	v_pk_mul_f32 v[86:87], v[86:87], v[148:149] op_sel_hi:[1,0]
	v_pk_mul_f32 v[72:73], v[80:81], v[148:149] op_sel_hi:[1,0]
	v_mul_f32_e32 v68, 0xbfb8aa3b, v87
	v_exp_f32_e32 v68, v68
	v_mov_b32_e32 v76, v69
	v_add_f32_e32 v68, 1.0, v68
	v_rcp_f32_e32 v68, v68
	s_nop 0
	v_mul_f32_e32 v68, v87, v68
	v_mul_f32_e32 v86, v86, v68
	v_mul_f32_e32 v68, 0xbfb8aa3b, v73
	v_exp_f32_e32 v68, v68
	s_nop 0
	v_add_f32_e32 v68, 1.0, v68
	v_rcp_f32_e32 v68, v68
	s_nop 0
	v_mul_f32_e32 v68, v73, v68
	v_mul_f32_e32 v80, v72, v68
	v_pk_mul_f32 v[68:69], v[76:77], v[148:149] op_sel_hi:[1,0]
	s_nop 0
	v_mul_f32_e32 v72, 0xbfb8aa3b, v69
	v_exp_f32_e32 v72, v72
	s_nop 0
	v_add_f32_e32 v72, 1.0, v72
	v_rcp_f32_e32 v72, v72
	s_nop 0
	v_mul_f32_e32 v69, v69, v72
	v_mul_f32_e32 v76, v68, v69
	v_mov_b32_e32 v68, v74
	v_mov_b32_e32 v69, v82
	v_pk_mul_f32 v[68:69], v[68:69], v[148:149] op_sel_hi:[1,0]
	v_mov_b32_e32 v82, v75
	v_mul_f32_e32 v72, 0xbfb8aa3b, v69
	v_exp_f32_e32 v72, v72
	s_nop 0
	v_add_f32_e32 v72, 1.0, v72
	v_rcp_f32_e32 v72, v72
	s_nop 0
	v_mul_f32_e32 v69, v69, v72
	v_mul_f32_e32 v74, v68, v69
	v_mov_b32_e32 v68, v70
	v_mov_b32_e32 v69, v78
	v_pk_mul_f32 v[68:69], v[68:69], v[148:149] op_sel_hi:[1,0]
	v_mov_b32_e32 v78, v71
	v_mul_f32_e32 v70, 0xbfb8aa3b, v69
	v_exp_f32_e32 v70, v70
	v_lshl_add_u64 v[72:73], v[84:85], 0, v[116:117]
	v_add_f32_e32 v70, 1.0, v70
	v_rcp_f32_e32 v70, v70
	s_nop 0
	v_mul_f32_e32 v69, v69, v70
	v_mul_f32_e32 v77, v68, v69
	v_pk_mul_f32 v[68:69], v[82:83], v[148:149] op_sel_hi:[1,0]
	s_nop 0
	v_mul_f32_e32 v70, 0xbfb8aa3b, v69
	v_exp_f32_e32 v70, v70
	s_nop 0
	v_add_f32_e32 v70, 1.0, v70
	v_rcp_f32_e32 v70, v70
	s_nop 0
	v_mul_f32_e32 v69, v69, v70
	v_mul_f32_e32 v70, v68, v69
	v_pk_mul_f32 v[68:69], v[78:79], v[148:149] op_sel_hi:[1,0]
	s_nop 0
	v_mul_f32_e32 v71, 0xbfb8aa3b, v69
	v_exp_f32_e32 v71, v71
	s_nop 0
	v_add_f32_e32 v71, 1.0, v71
	v_rcp_f32_e32 v71, v71
	s_nop 0
	v_mul_f32_e32 v69, v69, v71
	v_mul_f32_e32 v71, v68, v69
	v_cvt_pk_bf16_f32 v68, v88, v80
	v_cvt_pk_bf16_f32 v69, v74, v70
	v_cvt_pk_bf16_f32 v70, v86, v76
	v_cvt_pk_bf16_f32 v71, v77, v71
	global_store_dwordx4 v[72:73], v[68:71], off
	s_nop 1
	v_mov_b32_e32 v70, v56
	v_mov_b32_e32 v71, v64
	v_pk_mul_f32 v[70:71], v[70:71], v[146:147] op_sel_hi:[1,0]
	v_mov_b32_e32 v64, v57
	v_mul_f32_e32 v56, 0xbfb8aa3b, v71
	v_exp_f32_e32 v56, v56
	v_mad_i64_i32 v[68:69], s[4:5], v152, s18, v[134:135]
	v_add_f32_e32 v56, 1.0, v56
	v_rcp_f32_e32 v56, v56
	s_nop 0
	v_mul_f32_e32 v56, v71, v56
	v_mul_f32_e32 v72, v70, v56
	v_mov_b32_e32 v70, v52
	v_mov_b32_e32 v71, v60
	v_pk_mul_f32 v[70:71], v[70:71], v[146:147] op_sel_hi:[1,0]
	v_pk_mul_f32 v[56:57], v[64:65], v[146:147] op_sel_hi:[1,0]
	v_mul_f32_e32 v52, 0xbfb8aa3b, v71
	v_exp_f32_e32 v52, v52
	v_mov_b32_e32 v60, v53
	v_add_f32_e32 v52, 1.0, v52
	v_rcp_f32_e32 v52, v52
	s_nop 0
	v_mul_f32_e32 v52, v71, v52
	v_mul_f32_e32 v70, v70, v52
	v_mul_f32_e32 v52, 0xbfb8aa3b, v57
	v_exp_f32_e32 v52, v52
	s_nop 0
	v_add_f32_e32 v52, 1.0, v52
	v_rcp_f32_e32 v52, v52
	s_nop 0
	v_mul_f32_e32 v52, v57, v52
	v_mul_f32_e32 v64, v56, v52
	v_pk_mul_f32 v[52:53], v[60:61], v[146:147] op_sel_hi:[1,0]
	s_nop 0
	v_mul_f32_e32 v56, 0xbfb8aa3b, v53
	v_exp_f32_e32 v56, v56
	s_nop 0
	v_add_f32_e32 v56, 1.0, v56
	v_rcp_f32_e32 v56, v56
	s_nop 0
	v_mul_f32_e32 v53, v53, v56
	v_mul_f32_e32 v60, v52, v53
	v_mov_b32_e32 v52, v58
	v_mov_b32_e32 v53, v66
	v_pk_mul_f32 v[52:53], v[52:53], v[146:147] op_sel_hi:[1,0]
	v_mov_b32_e32 v66, v59
	v_mul_f32_e32 v56, 0xbfb8aa3b, v53
	v_exp_f32_e32 v56, v56
	s_nop 0
	v_add_f32_e32 v56, 1.0, v56
	v_rcp_f32_e32 v56, v56
	s_nop 0
	v_mul_f32_e32 v53, v53, v56
	v_mul_f32_e32 v58, v52, v53
	v_mov_b32_e32 v52, v54
	v_mov_b32_e32 v53, v62
	v_pk_mul_f32 v[52:53], v[52:53], v[146:147] op_sel_hi:[1,0]
	v_mov_b32_e32 v62, v55
	v_mul_f32_e32 v54, 0xbfb8aa3b, v53
	v_exp_f32_e32 v54, v54
	v_lshl_add_u64 v[56:57], v[68:69], 0, v[116:117]
	v_add_f32_e32 v54, 1.0, v54
	v_rcp_f32_e32 v54, v54
	s_nop 0
	v_mul_f32_e32 v53, v53, v54
	v_mul_f32_e32 v61, v52, v53
	v_pk_mul_f32 v[52:53], v[66:67], v[146:147] op_sel_hi:[1,0]
	s_nop 0
	v_mul_f32_e32 v54, 0xbfb8aa3b, v53
	v_exp_f32_e32 v54, v54
	s_nop 0
	v_add_f32_e32 v54, 1.0, v54
	v_rcp_f32_e32 v54, v54
	s_nop 0
	v_mul_f32_e32 v53, v53, v54
	v_mul_f32_e32 v54, v52, v53
	v_pk_mul_f32 v[52:53], v[62:63], v[146:147] op_sel_hi:[1,0]
	s_nop 0
	v_mul_f32_e32 v55, 0xbfb8aa3b, v53
	v_exp_f32_e32 v55, v55
	s_nop 0
	v_add_f32_e32 v55, 1.0, v55
	v_rcp_f32_e32 v55, v55
	s_nop 0
	v_mul_f32_e32 v53, v53, v55
	v_mul_f32_e32 v55, v52, v53
	v_cvt_pk_bf16_f32 v52, v72, v64
	v_cvt_pk_bf16_f32 v53, v58, v54
	v_cvt_pk_bf16_f32 v54, v70, v60
	v_cvt_pk_bf16_f32 v55, v61, v55
	global_store_dwordx4 v[56:57], v[52:55], off
	s_nop 1
	v_mov_b32_e32 v54, v40
	v_mov_b32_e32 v55, v48
	v_pk_mul_f32 v[54:55], v[54:55], v[160:161] op_sel_hi:[1,0]
	v_mov_b32_e32 v48, v41
	v_mul_f32_e32 v40, 0xbfb8aa3b, v55
	v_exp_f32_e32 v40, v40
	v_mad_i64_i32 v[52:53], s[4:5], v178, s18, v[134:135]
	v_add_f32_e32 v40, 1.0, v40
	v_rcp_f32_e32 v40, v40
	s_nop 0
	v_mul_f32_e32 v40, v55, v40
	v_mul_f32_e32 v56, v54, v40
	v_mov_b32_e32 v54, v36
	v_mov_b32_e32 v55, v44
	v_pk_mul_f32 v[54:55], v[54:55], v[160:161] op_sel_hi:[1,0]
	v_pk_mul_f32 v[40:41], v[48:49], v[160:161] op_sel_hi:[1,0]
	v_mul_f32_e32 v36, 0xbfb8aa3b, v55
	v_exp_f32_e32 v36, v36
	v_mov_b32_e32 v44, v37
	v_add_f32_e32 v36, 1.0, v36
	v_rcp_f32_e32 v36, v36
	s_nop 0
	v_mul_f32_e32 v36, v55, v36
	v_mul_f32_e32 v54, v54, v36
	v_mul_f32_e32 v36, 0xbfb8aa3b, v41
	v_exp_f32_e32 v36, v36
	s_nop 0
	v_add_f32_e32 v36, 1.0, v36
	v_rcp_f32_e32 v36, v36
	s_nop 0
	v_mul_f32_e32 v36, v41, v36
	v_mul_f32_e32 v48, v40, v36
	v_pk_mul_f32 v[36:37], v[44:45], v[160:161] op_sel_hi:[1,0]
	s_nop 0
	v_mul_f32_e32 v40, 0xbfb8aa3b, v37
	v_exp_f32_e32 v40, v40
	s_nop 0
	v_add_f32_e32 v40, 1.0, v40
	v_rcp_f32_e32 v40, v40
	s_nop 0
	v_mul_f32_e32 v37, v37, v40
	v_mul_f32_e32 v44, v36, v37
	v_mov_b32_e32 v36, v42
	v_mov_b32_e32 v37, v50
	v_pk_mul_f32 v[36:37], v[36:37], v[160:161] op_sel_hi:[1,0]
	v_mov_b32_e32 v50, v43
	v_mul_f32_e32 v40, 0xbfb8aa3b, v37
	v_exp_f32_e32 v40, v40
	s_nop 0
	v_add_f32_e32 v40, 1.0, v40
	v_rcp_f32_e32 v40, v40
	s_nop 0
	v_mul_f32_e32 v37, v37, v40
	v_mul_f32_e32 v42, v36, v37
	v_mov_b32_e32 v36, v38
	v_mov_b32_e32 v37, v46
	v_pk_mul_f32 v[36:37], v[36:37], v[160:161] op_sel_hi:[1,0]
	v_mov_b32_e32 v46, v39
	v_mul_f32_e32 v38, 0xbfb8aa3b, v37
	v_exp_f32_e32 v38, v38
	v_lshl_add_u64 v[40:41], v[52:53], 0, v[116:117]
	v_add_f32_e32 v38, 1.0, v38
	v_rcp_f32_e32 v38, v38
	s_nop 0
	v_mul_f32_e32 v37, v37, v38
	v_mul_f32_e32 v45, v36, v37
	v_pk_mul_f32 v[36:37], v[50:51], v[160:161] op_sel_hi:[1,0]
	s_nop 0
	v_mul_f32_e32 v38, 0xbfb8aa3b, v37
	v_exp_f32_e32 v38, v38
	s_nop 0
	v_add_f32_e32 v38, 1.0, v38
	v_rcp_f32_e32 v38, v38
	s_nop 0
	v_mul_f32_e32 v37, v37, v38
	v_mul_f32_e32 v38, v36, v37
	v_pk_mul_f32 v[36:37], v[46:47], v[160:161] op_sel_hi:[1,0]
	s_nop 0
	v_mul_f32_e32 v39, 0xbfb8aa3b, v37
	v_exp_f32_e32 v39, v39
	s_nop 0
	v_add_f32_e32 v39, 1.0, v39
	v_rcp_f32_e32 v39, v39
	s_nop 0
	v_mul_f32_e32 v37, v37, v39
	v_mul_f32_e32 v39, v36, v37
	v_cvt_pk_bf16_f32 v36, v56, v48
	v_cvt_pk_bf16_f32 v37, v42, v38
	v_cvt_pk_bf16_f32 v38, v54, v44
	v_cvt_pk_bf16_f32 v39, v45, v39
	global_store_dwordx4 v[40:41], v[36:39], off
	s_nop 1
	v_mov_b32_e32 v38, v24
	v_mov_b32_e32 v39, v32
	v_pk_mul_f32 v[38:39], v[38:39], v[164:165] op_sel_hi:[1,0]
	v_mov_b32_e32 v32, v25
	v_mul_f32_e32 v24, 0xbfb8aa3b, v39
	v_exp_f32_e32 v24, v24
	v_mad_i64_i32 v[36:37], s[4:5], v180, s18, v[134:135]
	v_add_f32_e32 v24, 1.0, v24
	v_rcp_f32_e32 v24, v24
	s_nop 0
	v_mul_f32_e32 v24, v39, v24
	v_mul_f32_e32 v40, v38, v24
	v_mov_b32_e32 v38, v20
	v_mov_b32_e32 v39, v28
	v_pk_mul_f32 v[38:39], v[38:39], v[164:165] op_sel_hi:[1,0]
	v_pk_mul_f32 v[24:25], v[32:33], v[164:165] op_sel_hi:[1,0]
	v_mul_f32_e32 v20, 0xbfb8aa3b, v39
	v_exp_f32_e32 v20, v20
	v_mov_b32_e32 v28, v21
	v_add_f32_e32 v20, 1.0, v20
	v_rcp_f32_e32 v20, v20
	s_nop 0
	v_mul_f32_e32 v20, v39, v20
	v_mul_f32_e32 v38, v38, v20
	v_mul_f32_e32 v20, 0xbfb8aa3b, v25
	v_exp_f32_e32 v20, v20
	s_nop 0
	v_add_f32_e32 v20, 1.0, v20
	v_rcp_f32_e32 v20, v20
	s_nop 0
	v_mul_f32_e32 v20, v25, v20
	v_mul_f32_e32 v32, v24, v20
	v_pk_mul_f32 v[20:21], v[28:29], v[164:165] op_sel_hi:[1,0]
	s_nop 0
	v_mul_f32_e32 v24, 0xbfb8aa3b, v21
	v_exp_f32_e32 v24, v24
	s_nop 0
	v_add_f32_e32 v24, 1.0, v24
	v_rcp_f32_e32 v24, v24
	s_nop 0
	v_mul_f32_e32 v21, v21, v24
	v_mul_f32_e32 v28, v20, v21
	v_mov_b32_e32 v20, v26
	v_mov_b32_e32 v21, v34
	v_pk_mul_f32 v[20:21], v[20:21], v[164:165] op_sel_hi:[1,0]
	v_mov_b32_e32 v34, v27
	v_mul_f32_e32 v24, 0xbfb8aa3b, v21
	v_exp_f32_e32 v24, v24
	s_nop 0
	v_add_f32_e32 v24, 1.0, v24
	v_rcp_f32_e32 v24, v24
	s_nop 0
	v_mul_f32_e32 v21, v21, v24
	v_mul_f32_e32 v26, v20, v21
	v_mov_b32_e32 v20, v22
	v_mov_b32_e32 v21, v30
	v_pk_mul_f32 v[20:21], v[20:21], v[164:165] op_sel_hi:[1,0]
	v_mov_b32_e32 v30, v23
	v_mul_f32_e32 v22, 0xbfb8aa3b, v21
	v_exp_f32_e32 v22, v22
	v_lshl_add_u64 v[24:25], v[36:37], 0, v[116:117]
	v_add_f32_e32 v22, 1.0, v22
	v_rcp_f32_e32 v22, v22
	s_nop 0
	v_mul_f32_e32 v21, v21, v22
	v_mul_f32_e32 v29, v20, v21
	v_pk_mul_f32 v[20:21], v[34:35], v[164:165] op_sel_hi:[1,0]
	s_nop 0
	v_mul_f32_e32 v22, 0xbfb8aa3b, v21
	v_exp_f32_e32 v22, v22
	s_nop 0
	v_add_f32_e32 v22, 1.0, v22
	v_rcp_f32_e32 v22, v22
	s_nop 0
	v_mul_f32_e32 v21, v21, v22
	v_mul_f32_e32 v22, v20, v21
	v_pk_mul_f32 v[20:21], v[30:31], v[164:165] op_sel_hi:[1,0]
	s_nop 0
	v_mul_f32_e32 v23, 0xbfb8aa3b, v21
	v_exp_f32_e32 v23, v23
	s_nop 0
	v_add_f32_e32 v23, 1.0, v23
	v_rcp_f32_e32 v23, v23
	s_nop 0
	v_mul_f32_e32 v21, v21, v23
	v_mul_f32_e32 v23, v20, v21
	v_cvt_pk_bf16_f32 v20, v40, v32
	v_cvt_pk_bf16_f32 v21, v26, v22
	v_cvt_pk_bf16_f32 v22, v38, v28
	v_cvt_pk_bf16_f32 v23, v29, v23
	global_store_dwordx4 v[24:25], v[20:23], off
	s_nop 1
	v_mov_b32_e32 v22, v8
	v_mov_b32_e32 v23, v16
	v_pk_mul_f32 v[22:23], v[22:23], v[132:133] op_sel_hi:[1,0]
	v_mov_b32_e32 v16, v9
	v_mul_f32_e32 v8, 0xbfb8aa3b, v23
	v_exp_f32_e32 v8, v8
	v_mad_i64_i32 v[20:21], s[4:5], v182, s18, v[134:135]
	s_mov_b64 s[4:5], -1
	v_add_f32_e32 v8, 1.0, v8
	v_rcp_f32_e32 v8, v8
	s_nop 0
	v_mul_f32_e32 v8, v23, v8
	v_mul_f32_e32 v24, v22, v8
	v_mov_b32_e32 v22, v4
	v_mov_b32_e32 v23, v12
	v_pk_mul_f32 v[22:23], v[22:23], v[132:133] op_sel_hi:[1,0]
	v_pk_mul_f32 v[8:9], v[16:17], v[132:133] op_sel_hi:[1,0]
	v_mul_f32_e32 v4, 0xbfb8aa3b, v23
	v_exp_f32_e32 v4, v4
	v_mov_b32_e32 v12, v5
	v_add_f32_e32 v4, 1.0, v4
	v_rcp_f32_e32 v4, v4
	s_nop 0
	v_mul_f32_e32 v4, v23, v4
	v_mul_f32_e32 v22, v22, v4
	v_mul_f32_e32 v4, 0xbfb8aa3b, v9
	v_exp_f32_e32 v4, v4
	s_nop 0
	v_add_f32_e32 v4, 1.0, v4
	v_rcp_f32_e32 v4, v4
	s_nop 0
	v_mul_f32_e32 v4, v9, v4
	v_mul_f32_e32 v16, v8, v4
	v_pk_mul_f32 v[4:5], v[12:13], v[132:133] op_sel_hi:[1,0]
	s_nop 0
	v_mul_f32_e32 v8, 0xbfb8aa3b, v5
	v_exp_f32_e32 v8, v8
	s_nop 0
	v_add_f32_e32 v8, 1.0, v8
	v_rcp_f32_e32 v8, v8
	s_nop 0
	v_mul_f32_e32 v5, v5, v8
	v_mul_f32_e32 v12, v4, v5
	v_mov_b32_e32 v4, v10
	v_mov_b32_e32 v5, v18
	v_pk_mul_f32 v[4:5], v[4:5], v[132:133] op_sel_hi:[1,0]
	v_mov_b32_e32 v18, v11
	v_mul_f32_e32 v8, 0xbfb8aa3b, v5
	v_exp_f32_e32 v8, v8
	s_nop 0
	v_add_f32_e32 v8, 1.0, v8
	v_rcp_f32_e32 v8, v8
	s_nop 0
	v_mul_f32_e32 v5, v5, v8
	v_mul_f32_e32 v10, v4, v5
	v_mov_b32_e32 v4, v6
	v_mov_b32_e32 v5, v14
	v_pk_mul_f32 v[4:5], v[4:5], v[132:133] op_sel_hi:[1,0]
	v_mov_b32_e32 v14, v7
	v_mul_f32_e32 v6, 0xbfb8aa3b, v5
	v_exp_f32_e32 v6, v6
	v_lshl_add_u64 v[8:9], v[20:21], 0, v[116:117]
	v_add_f32_e32 v6, 1.0, v6
	v_rcp_f32_e32 v6, v6
	s_nop 0
	v_mul_f32_e32 v5, v5, v6
	v_mul_f32_e32 v13, v4, v5
	v_pk_mul_f32 v[4:5], v[18:19], v[132:133] op_sel_hi:[1,0]
	s_nop 0
	v_mul_f32_e32 v6, 0xbfb8aa3b, v5
	v_exp_f32_e32 v6, v6
	s_nop 0
	v_add_f32_e32 v6, 1.0, v6
	v_rcp_f32_e32 v6, v6
	s_nop 0
	v_mul_f32_e32 v5, v5, v6
	v_mul_f32_e32 v6, v4, v5
	v_pk_mul_f32 v[4:5], v[14:15], v[132:133] op_sel_hi:[1,0]
	s_nop 0
	v_mul_f32_e32 v7, 0xbfb8aa3b, v5
	v_exp_f32_e32 v7, v7
	s_nop 0
	v_add_f32_e32 v7, 1.0, v7
	v_rcp_f32_e32 v7, v7
	s_nop 0
	v_mul_f32_e32 v5, v5, v7
	v_mul_f32_e32 v7, v4, v5
	v_cvt_pk_bf16_f32 v4, v24, v16
	v_cvt_pk_bf16_f32 v5, v10, v6
	v_cvt_pk_bf16_f32 v6, v22, v12
	v_cvt_pk_bf16_f32 v7, v13, v7
	global_store_dwordx4 v[8:9], v[4:7], off
	s_cbranch_vccnz .LBB0_859
	s_andn2_b64 vcc, exec, s[6:7]
	s_cbranch_vccnz .LBB0_858
	s_barrier
	s_branch .LBB0_858
